# P7 epilogue: rstd row sums computed once per tile via quarter loads + ds_bpermute gathers (same summation order), per-row 4-load reductions removed
# speedup vs baseline: 1.0205x; 1.0108x over previous
.LBB0_1467:
	v_lshl_add_u32 v138, s28, 8, v140
	v_ashrrev_i32_e32 v139, 31, v138
	v_lshlrev_b64 v[176:177], 6, v[138:139]
	v_lshl_add_u64 v[176:177], s[8:9], 0, v[176:177]
	v_and_b32_e32 v178, 48, v188
	v_mov_b32_e32 v179, 0
	s_mov_b64 s[98:99], 0x2000
	v_lshl_add_u64 v[176:177], v[176:177], 0, v[178:179]
	v_lshl_add_u64 v[178:179], v[176:177], 0, s[98:99]
	global_load_dwordx4 v[180:183], v[176:177], off
	global_load_dwordx4 v[184:187], v[176:177], off offset:1024
	global_load_dwordx4 v[192:195], v[176:177], off offset:2048
	global_load_dwordx4 v[196:199], v[176:177], off offset:3072
	global_load_dwordx4 v[200:203], v[178:179], off
	global_load_dwordx4 v[204:207], v[178:179], off offset:1024
	global_load_dwordx4 v[208:211], v[178:179], off offset:2048
	global_load_dwordx4 v[212:215], v[178:179], off offset:3072
	v_and_b32_e32 v174, 15, v188
	v_lshlrev_b32_e32 v216, 2, v174
	v_add_u32_e32 v217, 64, v216
	v_add_u32_e32 v218, 128, v216
	v_add_u32_e32 v219, 192, v216
	v_lshlrev_b64 v[148:149], 6, v[138:139]
	v_lshl_add_u64 v[160:161], s[8:9], 0, v[148:149]
	v_lshl_or_b32 v164, s26, 7, v142
	v_ashrrev_i32_e32 v165, 31, v164
	v_pk_mul_f32 v[166:167], v[122:123], v[114:115]
	v_lshlrev_b64 v[122:123], 1, v[164:165]
	v_pk_mul_f32 v[126:127], v[126:127], v[118:119]
	v_pk_mul_f32 v[124:125], v[124:125], v[116:117]
	v_pk_mul_f32 v[168:169], v[120:121], v[112:113]
	v_mov_b64_e32 v[120:121], s[10:11]
	v_or_b32_e32 v172, 16, v138
	v_mad_i64_i32 v[170:171], s[4:5], v138, s55, v[120:121]
	v_ashrrev_i32_e32 v173, 31, v172
	v_pk_mul_f32 v[110:111], v[110:111], v[102:103]
	v_pk_mul_f32 v[108:109], v[108:109], v[100:101]
	v_pk_mul_f32 v[106:107], v[106:107], v[98:99]
	v_pk_mul_f32 v[104:105], v[104:105], v[96:97]
	v_pk_mul_f32 v[94:95], v[94:95], v[86:87]
	v_pk_mul_f32 v[92:93], v[92:93], v[84:85]
	v_pk_mul_f32 v[90:91], v[90:91], v[82:83]
	v_pk_mul_f32 v[88:89], v[88:89], v[80:81]
	v_pk_mul_f32 v[78:79], v[78:79], v[70:71]
	v_pk_mul_f32 v[76:77], v[76:77], v[68:69]
	v_pk_mul_f32 v[74:75], v[74:75], v[66:67]
	v_pk_mul_f32 v[72:73], v[72:73], v[64:65]
	v_pk_mul_f32 v[62:63], v[62:63], v[54:55]
	v_pk_mul_f32 v[60:61], v[60:61], v[52:53]
	v_pk_mul_f32 v[58:59], v[58:59], v[50:51]
	v_pk_mul_f32 v[56:57], v[56:57], v[48:49]
	v_pk_mul_f32 v[46:47], v[46:47], v[38:39]
	v_pk_mul_f32 v[44:45], v[44:45], v[36:37]
	v_pk_mul_f32 v[42:43], v[42:43], v[34:35]
	v_pk_mul_f32 v[40:41], v[40:41], v[32:33]
	v_pk_mul_f32 v[30:31], v[30:31], v[22:23]
	v_pk_mul_f32 v[28:29], v[28:29], v[20:21]
	v_pk_mul_f32 v[26:27], v[26:27], v[18:19]
	v_pk_mul_f32 v[24:25], v[24:25], v[16:17]
	v_pk_mul_f32 v[14:15], v[14:15], v[6:7]
	v_pk_mul_f32 v[12:13], v[12:13], v[4:5]
	v_pk_mul_f32 v[10:11], v[10:11], v[2:3]
	v_pk_mul_f32 v[8:9], v[8:9], v[0:1]
	s_cmp_eq_u32 s45, s49
	s_waitcnt vmcnt(0)
	v_add_f32_e32 v180, v180, v181
	v_add_f32_e32 v182, v182, v183
	v_add_f32_e32 v184, v184, v185
	v_add_f32_e32 v186, v186, v187
	v_add_f32_e32 v192, v192, v193
	v_add_f32_e32 v194, v194, v195
	v_add_f32_e32 v196, v196, v197
	v_add_f32_e32 v198, v198, v199
	v_add_f32_e32 v200, v200, v201
	v_add_f32_e32 v202, v202, v203
	v_add_f32_e32 v204, v204, v205
	v_add_f32_e32 v206, v206, v207
	v_add_f32_e32 v208, v208, v209
	v_add_f32_e32 v210, v210, v211
	v_add_f32_e32 v212, v212, v213
	v_add_f32_e32 v214, v214, v215
	v_add_f32_e32 v180, v180, v182
	v_add_f32_e32 v184, v184, v186
	v_add_f32_e32 v192, v192, v194
	v_add_f32_e32 v196, v196, v198
	v_add_f32_e32 v200, v200, v202
	v_add_f32_e32 v204, v204, v206
	v_add_f32_e32 v208, v208, v210
	v_add_f32_e32 v212, v212, v214
	ds_bpermute_b32 v181, v216, v180
	ds_bpermute_b32 v185, v216, v184
	ds_bpermute_b32 v193, v216, v192
	ds_bpermute_b32 v197, v216, v196
	ds_bpermute_b32 v201, v216, v200
	ds_bpermute_b32 v205, v216, v204
	ds_bpermute_b32 v209, v216, v208
	ds_bpermute_b32 v213, v216, v212
	s_waitcnt lgkmcnt(0)
	ds_bpermute_b32 v182, v217, v180
	ds_bpermute_b32 v186, v217, v184
	ds_bpermute_b32 v194, v217, v192
	ds_bpermute_b32 v198, v217, v196
	ds_bpermute_b32 v202, v217, v200
	ds_bpermute_b32 v206, v217, v204
	ds_bpermute_b32 v210, v217, v208
	ds_bpermute_b32 v214, v217, v212
	s_waitcnt lgkmcnt(0)
	v_add_f32_e32 v181, v181, v182
	v_add_f32_e32 v185, v185, v186
	v_add_f32_e32 v193, v193, v194
	v_add_f32_e32 v197, v197, v198
	v_add_f32_e32 v201, v201, v202
	v_add_f32_e32 v205, v205, v206
	v_add_f32_e32 v209, v209, v210
	v_add_f32_e32 v213, v213, v214
	ds_bpermute_b32 v182, v218, v180
	ds_bpermute_b32 v186, v218, v184
	ds_bpermute_b32 v194, v218, v192
	ds_bpermute_b32 v198, v218, v196
	ds_bpermute_b32 v202, v218, v200
	ds_bpermute_b32 v206, v218, v204
	ds_bpermute_b32 v210, v218, v208
	ds_bpermute_b32 v214, v218, v212
	s_waitcnt lgkmcnt(0)
	v_add_f32_e32 v181, v181, v182
	v_add_f32_e32 v185, v185, v186
	v_add_f32_e32 v193, v193, v194
	v_add_f32_e32 v197, v197, v198
	v_add_f32_e32 v201, v201, v202
	v_add_f32_e32 v205, v205, v206
	v_add_f32_e32 v209, v209, v210
	v_add_f32_e32 v213, v213, v214
	ds_bpermute_b32 v182, v219, v180
	ds_bpermute_b32 v186, v219, v184
	ds_bpermute_b32 v194, v219, v192
	ds_bpermute_b32 v198, v219, v196
	ds_bpermute_b32 v202, v219, v200
	ds_bpermute_b32 v206, v219, v204
	ds_bpermute_b32 v210, v219, v208
	ds_bpermute_b32 v214, v219, v212
	s_waitcnt lgkmcnt(0)
	v_add_f32_e32 v181, v181, v182
	v_add_f32_e32 v185, v185, v186
	v_add_f32_e32 v193, v193, v194
	v_add_f32_e32 v197, v197, v198
	v_add_f32_e32 v201, v201, v202
	v_add_f32_e32 v205, v205, v206
	v_add_f32_e32 v209, v209, v210
	v_add_f32_e32 v213, v213, v214
	v_lshlrev_b64 v[150:151], 6, v[172:173]
	v_lshl_add_u64 v[150:151], s[8:9], 0, v[150:151]
	s_nop 1
	v_mov_b32_e32 v139, v181
	v_fmamk_f32 v139, v139, 0x3a800000, v146
	v_mul_f32_e32 v147, 0x4b800000, v139
	v_cmp_gt_f32_e32 vcc, s54, v139
	v_lshl_add_u64 v[148:149], v[170:171], 0, v[122:123]
	v_mad_i64_i32 v[154:155], s[4:5], v172, s55, v[120:121]
	v_cndmask_b32_e32 v139, v139, v147, vcc
	v_rsq_f32_e32 v139, v139
	s_nop 0
	v_mul_f32_e32 v147, 0x45800000, v139
	v_cndmask_b32_e32 v139, v139, v147, vcc
	v_mul_f32_e32 v147, 0xbfb8aa3b, v139
	v_mul_f32_e32 v139, v139, v139
	v_mul_f32_e32 v116, v116, v147
	v_mul_f32_e32 v117, v117, v147
	v_mul_f32_e32 v118, v118, v147
	v_mul_f32_e32 v119, v119, v147
	v_mul_f32_e32 v112, v112, v147
	v_mul_f32_e32 v113, v113, v147
	v_mul_f32_e32 v114, v114, v147
	v_mul_f32_e32 v115, v115, v147
	v_rcp_f32_e32 v139, v139
	v_exp_f32_e32 v116, v116
	v_exp_f32_e32 v117, v117
	v_exp_f32_e32 v118, v118
	v_exp_f32_e32 v119, v119
	v_exp_f32_e32 v112, v112
	v_exp_f32_e32 v113, v113
	v_exp_f32_e32 v114, v114
	v_exp_f32_e32 v115, v115
	v_fma_f32 v116, v116, v139, v139
	v_fma_f32 v117, v117, v139, v139
	v_fma_f32 v118, v118, v139, v139
	v_fma_f32 v119, v119, v139, v139
	v_fma_f32 v147, v112, v139, v139
	v_fma_f32 v152, v113, v139, v139
	v_fma_f32 v153, v114, v139, v139
	v_fmac_f32_e32 v139, v115, v139
	v_rcp_f32_e32 v112, v116
	v_rcp_f32_e32 v113, v117
	v_rcp_f32_e32 v114, v118
	v_rcp_f32_e32 v115, v119
	v_rcp_f32_e32 v116, v147
	v_rcp_f32_e32 v117, v152
	v_rcp_f32_e32 v118, v153
	v_rcp_f32_e32 v119, v139
	v_pk_mul_f32 v[112:113], v[124:125], v[112:113]
	v_pk_mul_f32 v[114:115], v[126:127], v[114:115]
	v_pk_mul_f32 v[116:117], v[168:169], v[116:117]
	v_pk_mul_f32 v[118:119], v[166:167], v[118:119]
	v_cvt_pk_bf16_f32 v112, v112, v113
	v_cvt_pk_bf16_f32 v113, v114, v115
	v_cvt_pk_bf16_f32 v114, v116, v117
	v_cvt_pk_bf16_f32 v115, v118, v119
	global_store_dwordx4 v[148:149], v[112:115], off
	v_or_b32_e32 v152, 32, v138
	v_ashrrev_i32_e32 v153, 31, v152
	v_lshlrev_b64 v[114:115], 6, v[152:153]
	v_lshl_add_u64 v[114:115], s[8:9], 0, v[114:115]
	s_nop 1
	v_mov_b32_e32 v112, v185
	v_fmamk_f32 v112, v112, 0x3a800000, v146
	v_mul_f32_e32 v113, 0x4b800000, v112
	v_cmp_gt_f32_e32 vcc, s54, v112
	s_nop 1
	v_cndmask_b32_e32 v112, v112, v113, vcc
	v_rsq_f32_e32 v116, v112
	v_lshl_add_u64 v[112:113], v[154:155], 0, v[122:123]
	v_mul_f32_e32 v117, 0x45800000, v116
	v_cndmask_b32_e32 v116, v116, v117, vcc
	v_mul_f32_e32 v117, 0xbfb8aa3b, v116
	v_mul_f32_e32 v116, v116, v116
	v_mul_f32_e32 v100, v100, v117
	v_mul_f32_e32 v101, v101, v117
	v_mul_f32_e32 v102, v102, v117
	v_mul_f32_e32 v103, v103, v117
	v_mul_f32_e32 v96, v96, v117
	v_mul_f32_e32 v97, v97, v117
	v_mul_f32_e32 v98, v98, v117
	v_mul_f32_e32 v99, v99, v117
	v_rcp_f32_e32 v116, v116
	v_exp_f32_e32 v100, v100
	v_exp_f32_e32 v101, v101
	v_exp_f32_e32 v102, v102
	v_exp_f32_e32 v103, v103
	v_exp_f32_e32 v96, v96
	v_exp_f32_e32 v97, v97
	v_exp_f32_e32 v98, v98
	v_exp_f32_e32 v99, v99
	v_fma_f32 v100, v100, v116, v116
	v_fma_f32 v101, v101, v116, v116
	v_fma_f32 v102, v102, v116, v116
	v_fma_f32 v103, v103, v116, v116
	v_fma_f32 v117, v96, v116, v116
	v_fma_f32 v118, v97, v116, v116
	v_fma_f32 v119, v98, v116, v116
	v_fmac_f32_e32 v116, v99, v116
	v_rcp_f32_e32 v96, v100
	v_rcp_f32_e32 v97, v101
	v_rcp_f32_e32 v98, v102
	v_rcp_f32_e32 v99, v103
	v_rcp_f32_e32 v100, v117
	v_rcp_f32_e32 v101, v118
	v_rcp_f32_e32 v102, v119
	v_rcp_f32_e32 v103, v116
	v_pk_mul_f32 v[96:97], v[108:109], v[96:97]
	v_pk_mul_f32 v[98:99], v[110:111], v[98:99]
	v_pk_mul_f32 v[100:101], v[104:105], v[100:101]
	v_pk_mul_f32 v[102:103], v[106:107], v[102:103]
	v_cvt_pk_bf16_f32 v96, v96, v97
	v_cvt_pk_bf16_f32 v97, v98, v99
	v_cvt_pk_bf16_f32 v98, v100, v101
	v_cvt_pk_bf16_f32 v99, v102, v103
	global_store_dwordx4 v[112:113], v[96:99], off
	v_or_b32_e32 v112, 48, v138
	v_mad_i64_i32 v[114:115], s[4:5], v152, s55, v[120:121]
	v_ashrrev_i32_e32 v113, 31, v112
	v_lshlrev_b64 v[98:99], 6, v[112:113]
	v_lshl_add_u64 v[98:99], s[8:9], 0, v[98:99]
	s_nop 1
	v_mov_b32_e32 v96, v193
	v_fmamk_f32 v96, v96, 0x3a800000, v146
	v_mul_f32_e32 v97, 0x4b800000, v96
	v_cmp_gt_f32_e32 vcc, s54, v96
	s_nop 1
	v_cndmask_b32_e32 v96, v96, v97, vcc
	v_rsq_f32_e32 v100, v96
	v_lshl_add_u64 v[96:97], v[114:115], 0, v[122:123]
	v_mul_f32_e32 v101, 0x45800000, v100
	v_cndmask_b32_e32 v100, v100, v101, vcc
	v_mul_f32_e32 v101, 0xbfb8aa3b, v100
	v_mul_f32_e32 v100, v100, v100
	v_mul_f32_e32 v84, v84, v101
	v_mul_f32_e32 v85, v85, v101
	v_mul_f32_e32 v86, v86, v101
	v_mul_f32_e32 v87, v87, v101
	v_mul_f32_e32 v80, v80, v101
	v_mul_f32_e32 v81, v81, v101
	v_mul_f32_e32 v82, v82, v101
	v_mul_f32_e32 v83, v83, v101
	v_rcp_f32_e32 v100, v100
	v_exp_f32_e32 v84, v84
	v_exp_f32_e32 v85, v85
	v_exp_f32_e32 v86, v86
	v_exp_f32_e32 v87, v87
	v_exp_f32_e32 v80, v80
	v_exp_f32_e32 v81, v81
	v_exp_f32_e32 v82, v82
	v_exp_f32_e32 v83, v83
	v_fma_f32 v84, v84, v100, v100
	v_fma_f32 v85, v85, v100, v100
	v_fma_f32 v86, v86, v100, v100
	v_fma_f32 v87, v87, v100, v100
	v_fma_f32 v101, v80, v100, v100
	v_fma_f32 v102, v81, v100, v100
	v_fma_f32 v103, v82, v100, v100
	v_fmac_f32_e32 v100, v83, v100
	v_rcp_f32_e32 v80, v84
	v_rcp_f32_e32 v81, v85
	v_rcp_f32_e32 v82, v86
	v_rcp_f32_e32 v83, v87
	v_rcp_f32_e32 v84, v101
	v_rcp_f32_e32 v85, v102
	v_rcp_f32_e32 v86, v103
	v_rcp_f32_e32 v87, v100
	v_pk_mul_f32 v[80:81], v[92:93], v[80:81]
	v_pk_mul_f32 v[82:83], v[94:95], v[82:83]
	v_pk_mul_f32 v[84:85], v[88:89], v[84:85]
	v_pk_mul_f32 v[86:87], v[90:91], v[86:87]
	v_cvt_pk_bf16_f32 v80, v80, v81
	v_cvt_pk_bf16_f32 v81, v82, v83
	v_cvt_pk_bf16_f32 v82, v84, v85
	v_cvt_pk_bf16_f32 v83, v86, v87
	global_store_dwordx4 v[96:97], v[80:83], off
	v_add_u32_e32 v96, 0x80, v138
	v_mad_i64_i32 v[98:99], s[4:5], v112, s55, v[120:121]
	v_ashrrev_i32_e32 v97, 31, v96
	v_lshlrev_b64 v[82:83], 6, v[96:97]
	v_lshl_add_u64 v[82:83], s[8:9], 0, v[82:83]
	s_nop 1
	v_mov_b32_e32 v80, v197
	v_fmamk_f32 v80, v80, 0x3a800000, v146
	v_mul_f32_e32 v81, 0x4b800000, v80
	v_cmp_gt_f32_e32 vcc, s54, v80
	s_nop 1
	v_cndmask_b32_e32 v80, v80, v81, vcc
	v_rsq_f32_e32 v84, v80
	v_lshl_add_u64 v[80:81], v[98:99], 0, v[122:123]
	v_mul_f32_e32 v85, 0x45800000, v84
	v_cndmask_b32_e32 v84, v84, v85, vcc
	v_mul_f32_e32 v85, 0xbfb8aa3b, v84
	v_mul_f32_e32 v84, v84, v84
	v_mul_f32_e32 v68, v68, v85
	v_mul_f32_e32 v69, v69, v85
	v_mul_f32_e32 v70, v70, v85
	v_mul_f32_e32 v71, v71, v85
	v_mul_f32_e32 v64, v64, v85
	v_mul_f32_e32 v65, v65, v85
	v_mul_f32_e32 v66, v66, v85
	v_mul_f32_e32 v67, v67, v85
	v_rcp_f32_e32 v84, v84
	v_exp_f32_e32 v68, v68
	v_exp_f32_e32 v69, v69
	v_exp_f32_e32 v70, v70
	v_exp_f32_e32 v71, v71
	v_exp_f32_e32 v64, v64
	v_exp_f32_e32 v65, v65
	v_exp_f32_e32 v66, v66
	v_exp_f32_e32 v67, v67
	v_fma_f32 v68, v68, v84, v84
	v_fma_f32 v69, v69, v84, v84
	v_fma_f32 v70, v70, v84, v84
	v_fma_f32 v71, v71, v84, v84
	v_fma_f32 v85, v64, v84, v84
	v_fma_f32 v86, v65, v84, v84
	v_fma_f32 v87, v66, v84, v84
	v_fmac_f32_e32 v84, v67, v84
	v_rcp_f32_e32 v64, v68
	v_rcp_f32_e32 v65, v69
	v_rcp_f32_e32 v66, v70
	v_rcp_f32_e32 v67, v71
	v_rcp_f32_e32 v68, v85
	v_rcp_f32_e32 v69, v86
	v_rcp_f32_e32 v70, v87
	v_rcp_f32_e32 v71, v84
	v_pk_mul_f32 v[64:65], v[76:77], v[64:65]
	v_pk_mul_f32 v[66:67], v[78:79], v[66:67]
	v_pk_mul_f32 v[68:69], v[72:73], v[68:69]
	v_pk_mul_f32 v[70:71], v[74:75], v[70:71]
	v_cvt_pk_bf16_f32 v64, v64, v65
	v_cvt_pk_bf16_f32 v65, v66, v67
	v_cvt_pk_bf16_f32 v66, v68, v69
	v_cvt_pk_bf16_f32 v67, v70, v71
	global_store_dwordx4 v[80:81], v[64:67], off
	v_add_u32_e32 v80, 0x90, v138
	v_mad_i64_i32 v[82:83], s[4:5], v96, s55, v[120:121]
	v_ashrrev_i32_e32 v81, 31, v80
	v_lshlrev_b64 v[66:67], 6, v[80:81]
	v_lshl_add_u64 v[66:67], s[8:9], 0, v[66:67]
	s_nop 1
	v_mov_b32_e32 v64, v201
	v_fmamk_f32 v64, v64, 0x3a800000, v146
	v_mul_f32_e32 v65, 0x4b800000, v64
	v_cmp_gt_f32_e32 vcc, s54, v64
	s_nop 1
	v_cndmask_b32_e32 v64, v64, v65, vcc
	v_rsq_f32_e32 v68, v64
	v_lshl_add_u64 v[64:65], v[82:83], 0, v[122:123]
	v_mul_f32_e32 v69, 0x45800000, v68
	v_cndmask_b32_e32 v68, v68, v69, vcc
	v_mul_f32_e32 v69, 0xbfb8aa3b, v68
	v_mul_f32_e32 v68, v68, v68
	v_mul_f32_e32 v52, v52, v69
	v_mul_f32_e32 v53, v53, v69
	v_mul_f32_e32 v54, v54, v69
	v_mul_f32_e32 v55, v55, v69
	v_mul_f32_e32 v48, v48, v69
	v_mul_f32_e32 v49, v49, v69
	v_mul_f32_e32 v50, v50, v69
	v_mul_f32_e32 v51, v51, v69
	v_rcp_f32_e32 v68, v68
	v_exp_f32_e32 v52, v52
	v_exp_f32_e32 v53, v53
	v_exp_f32_e32 v54, v54
	v_exp_f32_e32 v55, v55
	v_exp_f32_e32 v48, v48
	v_exp_f32_e32 v49, v49
	v_exp_f32_e32 v50, v50
	v_exp_f32_e32 v51, v51
	v_fma_f32 v52, v52, v68, v68
	v_fma_f32 v53, v53, v68, v68
	v_fma_f32 v54, v54, v68, v68
	v_fma_f32 v55, v55, v68, v68
	v_fma_f32 v69, v48, v68, v68
	v_fma_f32 v70, v49, v68, v68
	v_fma_f32 v71, v50, v68, v68
	v_fmac_f32_e32 v68, v51, v68
	v_rcp_f32_e32 v48, v52
	v_rcp_f32_e32 v49, v53
	v_rcp_f32_e32 v50, v54
	v_rcp_f32_e32 v51, v55
	v_rcp_f32_e32 v52, v69
	v_rcp_f32_e32 v53, v70
	v_rcp_f32_e32 v54, v71
	v_rcp_f32_e32 v55, v68
	v_pk_mul_f32 v[48:49], v[60:61], v[48:49]
	v_pk_mul_f32 v[50:51], v[62:63], v[50:51]
	v_pk_mul_f32 v[52:53], v[56:57], v[52:53]
	v_pk_mul_f32 v[54:55], v[58:59], v[54:55]
	v_cvt_pk_bf16_f32 v48, v48, v49
	v_cvt_pk_bf16_f32 v49, v50, v51
	v_cvt_pk_bf16_f32 v50, v52, v53
	v_cvt_pk_bf16_f32 v51, v54, v55
	global_store_dwordx4 v[64:65], v[48:51], off
	v_add_u32_e32 v64, 0xa0, v138
	v_mad_i64_i32 v[66:67], s[4:5], v80, s55, v[120:121]
	v_ashrrev_i32_e32 v65, 31, v64
	v_lshlrev_b64 v[50:51], 6, v[64:65]
	v_lshl_add_u64 v[50:51], s[8:9], 0, v[50:51]
	s_nop 1
	v_mov_b32_e32 v48, v205
	v_fmamk_f32 v48, v48, 0x3a800000, v146
	v_mul_f32_e32 v49, 0x4b800000, v48
	v_cmp_gt_f32_e32 vcc, s54, v48
	s_nop 1
	v_cndmask_b32_e32 v48, v48, v49, vcc
	v_rsq_f32_e32 v52, v48
	v_lshl_add_u64 v[48:49], v[66:67], 0, v[122:123]
	v_mul_f32_e32 v53, 0x45800000, v52
	v_cndmask_b32_e32 v52, v52, v53, vcc
	v_mul_f32_e32 v53, 0xbfb8aa3b, v52
	v_mul_f32_e32 v52, v52, v52
	v_mul_f32_e32 v36, v36, v53
	v_mul_f32_e32 v37, v37, v53
	v_mul_f32_e32 v38, v38, v53
	v_mul_f32_e32 v39, v39, v53
	v_mul_f32_e32 v32, v32, v53
	v_mul_f32_e32 v33, v33, v53
	v_mul_f32_e32 v34, v34, v53
	v_mul_f32_e32 v35, v35, v53
	v_rcp_f32_e32 v52, v52
	v_exp_f32_e32 v36, v36
	v_exp_f32_e32 v37, v37
	v_exp_f32_e32 v38, v38
	v_exp_f32_e32 v39, v39
	v_exp_f32_e32 v32, v32
	v_exp_f32_e32 v33, v33
	v_exp_f32_e32 v34, v34
	v_exp_f32_e32 v35, v35
	v_fma_f32 v36, v36, v52, v52
	v_fma_f32 v37, v37, v52, v52
	v_fma_f32 v38, v38, v52, v52
	v_fma_f32 v39, v39, v52, v52
	v_fma_f32 v53, v32, v52, v52
	v_fma_f32 v54, v33, v52, v52
	v_fma_f32 v55, v34, v52, v52
	v_fmac_f32_e32 v52, v35, v52
	v_rcp_f32_e32 v32, v36
	v_rcp_f32_e32 v33, v37
	v_rcp_f32_e32 v34, v38
	v_rcp_f32_e32 v35, v39
	v_rcp_f32_e32 v36, v53
	v_rcp_f32_e32 v37, v54
	v_rcp_f32_e32 v38, v55
	v_rcp_f32_e32 v39, v52
	v_pk_mul_f32 v[32:33], v[44:45], v[32:33]
	v_pk_mul_f32 v[34:35], v[46:47], v[34:35]
	v_pk_mul_f32 v[36:37], v[40:41], v[36:37]
	v_pk_mul_f32 v[38:39], v[42:43], v[38:39]
	v_cvt_pk_bf16_f32 v32, v32, v33
	v_cvt_pk_bf16_f32 v33, v34, v35
	v_cvt_pk_bf16_f32 v34, v36, v37
	v_cvt_pk_bf16_f32 v35, v38, v39
	global_store_dwordx4 v[48:49], v[32:35], off
	v_add_u32_e32 v48, 0xb0, v138
	v_mad_i64_i32 v[50:51], s[4:5], v64, s55, v[120:121]
	v_ashrrev_i32_e32 v49, 31, v48
	v_lshlrev_b64 v[34:35], 6, v[48:49]
	v_lshl_add_u64 v[34:35], s[8:9], 0, v[34:35]
	s_nop 1
	v_mov_b32_e32 v32, v209
	v_fmamk_f32 v32, v32, 0x3a800000, v146
	v_mul_f32_e32 v33, 0x4b800000, v32
	v_cmp_gt_f32_e32 vcc, s54, v32
	s_nop 1
	v_cndmask_b32_e32 v32, v32, v33, vcc
	v_rsq_f32_e32 v36, v32
	v_lshl_add_u64 v[32:33], v[50:51], 0, v[122:123]
	v_mul_f32_e32 v37, 0x45800000, v36
	v_cndmask_b32_e32 v36, v36, v37, vcc
	v_mul_f32_e32 v37, 0xbfb8aa3b, v36
	v_mul_f32_e32 v36, v36, v36
	v_mul_f32_e32 v20, v20, v37
	v_mul_f32_e32 v21, v21, v37
	v_mul_f32_e32 v22, v22, v37
	v_mul_f32_e32 v23, v23, v37
	v_mul_f32_e32 v16, v16, v37
	v_mul_f32_e32 v17, v17, v37
	v_mul_f32_e32 v18, v18, v37
	v_mul_f32_e32 v19, v19, v37
	v_rcp_f32_e32 v36, v36
	v_exp_f32_e32 v20, v20
	v_exp_f32_e32 v21, v21
	v_exp_f32_e32 v22, v22
	v_exp_f32_e32 v23, v23
	v_exp_f32_e32 v16, v16
	v_exp_f32_e32 v17, v17
	v_exp_f32_e32 v18, v18
	v_exp_f32_e32 v19, v19
	v_fma_f32 v20, v20, v36, v36
	v_fma_f32 v21, v21, v36, v36
	v_fma_f32 v22, v22, v36, v36
	v_fma_f32 v23, v23, v36, v36
	v_fma_f32 v37, v16, v36, v36
	v_fma_f32 v38, v17, v36, v36
	v_fma_f32 v39, v18, v36, v36
	v_fmac_f32_e32 v36, v19, v36
	v_rcp_f32_e32 v16, v20
	v_rcp_f32_e32 v17, v21
	v_rcp_f32_e32 v18, v22
	v_rcp_f32_e32 v19, v23
	v_rcp_f32_e32 v20, v37
	v_rcp_f32_e32 v21, v38
	v_rcp_f32_e32 v22, v39
	v_rcp_f32_e32 v23, v36
	v_pk_mul_f32 v[16:17], v[28:29], v[16:17]
	v_pk_mul_f32 v[18:19], v[30:31], v[18:19]
	v_pk_mul_f32 v[20:21], v[24:25], v[20:21]
	v_pk_mul_f32 v[22:23], v[26:27], v[22:23]
	v_cvt_pk_bf16_f32 v16, v16, v17
	v_cvt_pk_bf16_f32 v17, v18, v19
	v_cvt_pk_bf16_f32 v18, v20, v21
	v_cvt_pk_bf16_f32 v19, v22, v23
	global_store_dwordx4 v[32:33], v[16:19], off
	s_nop 1
	v_mov_b32_e32 v16, v213
	v_fmamk_f32 v16, v16, 0x3a800000, v146
	v_mul_f32_e32 v17, 0x4b800000, v16
	v_cmp_gt_f32_e32 vcc, s54, v16
	s_nop 1
	v_cndmask_b32_e32 v16, v16, v17, vcc
	v_rsq_f32_e32 v18, v16
	v_mad_i64_i32 v[16:17], s[4:5], v48, s55, v[120:121]
	v_lshl_add_u64 v[16:17], v[16:17], 0, v[122:123]
	v_mul_f32_e32 v19, 0x45800000, v18
	v_cndmask_b32_e32 v18, v18, v19, vcc
	v_mul_f32_e32 v19, 0xbfb8aa3b, v18
	v_mul_f32_e32 v18, v18, v18
	v_mul_f32_e32 v4, v4, v19
	v_mul_f32_e32 v5, v5, v19
	v_mul_f32_e32 v6, v6, v19
	v_mul_f32_e32 v7, v7, v19
	v_mul_f32_e32 v0, v0, v19
	v_mul_f32_e32 v1, v1, v19
	v_mul_f32_e32 v2, v2, v19
	v_mul_f32_e32 v3, v3, v19
	v_rcp_f32_e32 v18, v18
	v_exp_f32_e32 v4, v4
	v_exp_f32_e32 v5, v5
	v_exp_f32_e32 v6, v6
	v_exp_f32_e32 v7, v7
	v_exp_f32_e32 v0, v0
	v_exp_f32_e32 v1, v1
	v_exp_f32_e32 v2, v2
	v_exp_f32_e32 v3, v3
	v_fma_f32 v4, v4, v18, v18
	v_fma_f32 v5, v5, v18, v18
	v_fma_f32 v6, v6, v18, v18
	v_fma_f32 v7, v7, v18, v18
	v_fma_f32 v19, v0, v18, v18
	v_fma_f32 v20, v1, v18, v18
	v_fma_f32 v21, v2, v18, v18
	v_fmac_f32_e32 v18, v3, v18
	v_rcp_f32_e32 v0, v4
	v_rcp_f32_e32 v1, v5
	v_rcp_f32_e32 v2, v6
	v_rcp_f32_e32 v3, v7
	v_rcp_f32_e32 v4, v19
	v_rcp_f32_e32 v5, v20
	v_rcp_f32_e32 v6, v21
	v_rcp_f32_e32 v7, v18
	v_pk_mul_f32 v[0:1], v[12:13], v[0:1]
	v_pk_mul_f32 v[2:3], v[14:15], v[2:3]
	v_pk_mul_f32 v[4:5], v[8:9], v[4:5]
	v_pk_mul_f32 v[6:7], v[10:11], v[6:7]
	v_cvt_pk_bf16_f32 v0, v0, v1
	v_cvt_pk_bf16_f32 v1, v2, v3
	v_cvt_pk_bf16_f32 v2, v4, v5
	v_cvt_pk_bf16_f32 v3, v6, v7
	s_mov_b64 s[4:5], -1
	global_store_dwordx4 v[16:17], v[0:3], off
	s_cbranch_scc1 .LBB0_1457
	s_andn2_b64 vcc, exec, s[6:7]
	s_cbranch_vccnz .LBB0_1456
	s_barrier
	s_branch .LBB0_1456

	.amdhsa_kernel _Z10fwd_kernel4Args
		.amdhsa_group_segment_fixed_size 0
		.amdhsa_private_segment_fixed_size 0
		.amdhsa_kernarg_size 528
		.amdhsa_user_sgpr_count 2
		.amdhsa_user_sgpr_dispatch_ptr 0
		.amdhsa_user_sgpr_queue_ptr 0
		.amdhsa_user_sgpr_kernarg_segment_ptr 1
		.amdhsa_user_sgpr_dispatch_id 0
		.amdhsa_user_sgpr_kernarg_preload_length 0
		.amdhsa_user_sgpr_kernarg_preload_offset 0
		.amdhsa_user_sgpr_private_segment_size 0
		.amdhsa_uses_dynamic_stack 0
		.amdhsa_enable_private_segment 0
		.amdhsa_system_sgpr_workgroup_id_x 1
		.amdhsa_system_sgpr_workgroup_id_y 0
		.amdhsa_system_sgpr_workgroup_id_z 0
		.amdhsa_system_sgpr_workgroup_info 0
		.amdhsa_system_vgpr_workitem_id 2
		.amdhsa_next_free_vgpr 241
		.amdhsa_next_free_sgpr 102
		.amdhsa_accum_offset 244
		.amdhsa_reserve_vcc 1
		.amdhsa_float_round_mode_32 0
		.amdhsa_float_round_mode_16_64 0
		.amdhsa_float_denorm_mode_32 3
		.amdhsa_float_denorm_mode_16_64 3
		.amdhsa_dx10_clamp 1
		.amdhsa_ieee_mode 1
		.amdhsa_fp16_overflow 0
		.amdhsa_tg_split 0
		.amdhsa_exception_fp_ieee_invalid_op 0
		.amdhsa_exception_fp_denorm_src 0
		.amdhsa_exception_fp_ieee_div_zero 0
		.amdhsa_exception_fp_ieee_overflow 0
		.amdhsa_exception_fp_ieee_underflow 0
		.amdhsa_exception_fp_ieee_inexact 0
		.amdhsa_exception_int_div_zero 0
	.end_amdhsa_kernel

amdhsa.kernels:
  - .agpr_count:     0
    .args:
      - .offset:         0
        .size:           272
        .value_kind:     by_value
      - .offset:         272
        .size:           4
        .value_kind:     hidden_block_count_x
      - .offset:         276
        .size:           4
        .value_kind:     hidden_block_count_y
      - .offset:         280
        .size:           4
        .value_kind:     hidden_block_count_z
      - .offset:         284
        .size:           2
        .value_kind:     hidden_group_size_x
      - .offset:         286
        .size:           2
        .value_kind:     hidden_group_size_y
      - .offset:         288
        .size:           2
        .value_kind:     hidden_group_size_z
      - .offset:         290
        .size:           2
        .value_kind:     hidden_remainder_x
      - .offset:         292
        .size:           2
        .value_kind:     hidden_remainder_y
      - .offset:         294
        .size:           2
        .value_kind:     hidden_remainder_z
      - .offset:         312
        .size:           8
        .value_kind:     hidden_global_offset_x
      - .offset:         320
        .size:           8
        .value_kind:     hidden_global_offset_y
      - .offset:         328
        .size:           8
        .value_kind:     hidden_global_offset_z
      - .offset:         336
        .size:           2
        .value_kind:     hidden_grid_dims
      - .offset:         360
        .size:           8
        .value_kind:     hidden_multigrid_sync_arg
      - .offset:         392
        .size:           4
        .value_kind:     hidden_dynamic_lds_size
    .group_segment_fixed_size: 0
    .kernarg_segment_align: 8
    .kernarg_segment_size: 528
    .language:       OpenCL C
    .language_version:
      - 2
      - 0
    .max_flat_workgroup_size: 512
    .name:           _Z10fwd_kernel4Args
    .private_segment_fixed_size: 0
    .sgpr_count:     108
    .sgpr_spill_count: 67
    .symbol:         _Z10fwd_kernel4Args.kd
    .uniform_work_group_size: 1
    .uses_dynamic_stack: false
    .vgpr_count:     241
    .vgpr_spill_count: 0
    .wavefront_size: 64
